# v56 + RWKV staging: transposed bf16 images written as dwords (two tokens of one channel via v_permlane32_swap) - 4 b32 instead of 8 conflicting b16 writes
# speedup vs baseline: 1.0066x; 1.0066x over previous
; #define LAS __attribute__((address_space(3)))
; __device__ __forceinline__ void rwkv_chunk_item(const P& p, const Ctx& c, int seg, int w, bool save) {
;     ...
;     auto lstore = [&](int pb, int tidv) { const int t = tidv >> 5, j0 = (tidv & 31) * 2;
;         LAS bf16_t* EA = (LAS bf16_t*)(OB + pb * OPB + O_EA); LAS bf16_t* EB = (LAS bf16_t*)(OB + pb * OPB + O_EB); LAS bf16_t* EBT = (LAS bf16_t*)(OB + pb * OPB + O_EBT);
;         LAS bf16_t* UV = (LAS bf16_t*)(OB + pb * OPB + O_UV); LAS float* GT = (LAS float*)(OB + pb * OPB + O_GT);
;         *(LAS unsigned*)(EA + t * 72 + j0) = ga; *(LAS unsigned*)(EA + (16 + t) * 72 + j0) = gr;
;         *(LAS unsigned*)(EB + t * 72 + j0) = gb; *(LAS unsigned*)(EB + (16 + t) * 72 + j0) = gk;
;         EBT[j0 * 40 + t] = (bf16_t)(gb & 0xFFFFu); EBT[(j0 + 1) * 40 + t] = (bf16_t)(gb >> 16); EBT[j0 * 40 + 16 + t] = (bf16_t)(gk & 0xFFFFu); EBT[(j0 + 1) * 40 + 16 + t] = (bf16_t)(gk >> 16);
;         UV[j0 * 40 + 16 + t] = (bf16_t)(gv & 0xFFFFu); UV[(j0 + 1) * 40 + 16 + t] = (bf16_t)(gv >> 16); UV[j0 * 40 + t] = 0; UV[(j0 + 1) * 40 + t] = 0;
;         if (tidv < 64) GT[tidv] = gg; };
.Lrw_early_skip:
	s_cmp_eq_u32 s86, 31
	s_cselect_b64 s[4:5], -1, 0
	s_and_b64 vcc, exec, s[4:5]
	v_ashrrev_i32_e32 v46, 5, v44
	v_lshlrev_b32_e32 v45, 1, v44
	v_cmp_gt_i32_e64 s[2:3], 64, v44
	s_cbranch_vccnz .LBB0_931
	s_xor_b32 s78, s87, 1
	v_and_b32_e32 v47, 62, v45
	s_mulk_i32 s78, 0x5c00
	s_add_i32 s89, s78, 0
	v_mul_lo_u32 v48, v46, s63
	v_lshlrev_b32_e32 v49, 1, v47
	v_mad_u32_u24 v47, v47, 40, v46
	v_add3_u32 v48, s89, v48, v49
	v_lshl_add_u32 v47, v47, 1, s89
	s_waitcnt vmcnt(0)
	ds_write2st64_b32 v48, v71, v76 offset1:9
	ds_write2st64_b32 v48, v74, v75 offset0:18 offset1:27
	v_bfe_u32 v104, v44, 5, 1
	v_cmp_ne_u32_e32 vcc, 0, v104
	v_mov_b32_e32 v105, 0x5040100
	v_mov_b32_e32 v106, 0x7060302
	v_mul_u32_u24_e32 v104, 0x4e, v104
	v_cndmask_b32_e32 v105, v105, v106, vcc
	v_add_u32_e32 v104, v47, v104
	v_mov_b32_e32 v106, v74
	v_mov_b32_e32 v107, v74
	s_nop 1
	v_permlane32_swap_b32_e32 v106, v107
	v_perm_b32 v108, v107, v106, v105
	ds_write_b32 v104, v108 offset:9216
	v_mov_b32_e32 v106, v75
	v_mov_b32_e32 v107, v75
	s_nop 1
	v_permlane32_swap_b32_e32 v106, v107
	v_perm_b32 v108, v107, v106, v105
	ds_write_b32 v104, v108 offset:9248
	v_mov_b32_e32 v106, v79
	v_mov_b32_e32 v107, v79
	s_nop 1
	v_permlane32_swap_b32_e32 v106, v107
	v_perm_b32 v108, v107, v106, v105
	ds_write_b32 v104, v108 offset:14368
	ds_write_b32 v104, v5 offset:14336
	s_and_saveexec_b64 s[78:79], s[2:3]
	v_lshl_add_u32 v47, v44, 2, s89
	ds_write_b32 v47, v27 offset:23296
	s_or_b64 exec, exec, s[78:79]
	s_cmp_gt_u32 s86, 29
	s_cbranch_scc0 .LBB0_932

; #define LAS __attribute__((address_space(3)))
; __device__ __forceinline__ unsigned pk2(float lo, float hi) { const bf2_t r = __builtin_convertvector((f32x2){lo, hi}, bf2_t); unsigned u; __builtin_memcpy(&u, &r, 4); return u; }
; __device__ __forceinline__ void rwkv_chunk_item(const P& p, const Ctx& c, int seg, int w, bool save) {
;     ...
;         if (c.wv == 0) {
;             float u[16];
; #pragma unroll
;             for (int p2 = 0; p2 < 8; ++p2) { f32x2 acc = (f32x2){XF[c.lane * 17 + 2 * p2], XF[c.lane * 17 + 2 * p2 + 1]};
; #pragma unroll
;                 for (int s2 = 0; s2 < 2 * p2; ++s2) { const f32x2 m = *(const LAS f32x2*)(MABT + s2 * 20 + 2 * p2); acc += (f32x2){u[s2], u[s2]} * m; }
;                 u[2 * p2] = acc.x;
;                 u[2 * p2 + 1] = acc.y + acc.x * MABT[(2 * p2) * 20 + 2 * p2 + 1]; }
;             *(LAS u32x4*)(UV + c.lane * 40) = (u32x4){pk2(u[0], u[1]), pk2(u[2], u[3]), pk2(u[4], u[5]), pk2(u[6], u[7])};
;             *(LAS u32x4*)(UV + c.lane * 40 + 8) = (u32x4){pk2(u[8], u[9]), pk2(u[10], u[11]), pk2(u[12], u[13]), pk2(u[14], u[15])};
;         }
.LBB0_895:
	s_waitcnt lgkmcnt(7)
	v_fma_f32 v46, v170, v100, v101
	v_pk_fma_f32 v[102:103], v[100:101], v[156:157], v[102:103] op_sel_hi:[0,1,1]
	v_pk_fma_f32 v[52:53], v[100:101], v[230:231], v[52:53] op_sel_hi:[0,1,1]
	v_pk_fma_f32 v[56:57], v[100:101], v[232:233], v[56:57] op_sel_hi:[0,1,1]
	v_pk_fma_f32 v[60:61], v[100:101], v[124:125], v[60:61] op_sel_hi:[0,1,1]
	v_pk_fma_f32 v[64:65], v[100:101], v[126:127], v[64:65] op_sel_hi:[0,1,1]
	v_pk_fma_f32 v[68:69], v[100:101], v[176:177], v[68:69] op_sel_hi:[0,1,1]
	v_pk_fma_f32 v[72:73], v[100:101], v[178:179], v[72:73] op_sel_hi:[0,1,1]
	v_pk_fma_f32 v[102:103], v[46:47], v[158:159], v[102:103] op_sel_hi:[0,1,1]
	v_pk_fma_f32 v[52:53], v[46:47], v[234:235], v[52:53] op_sel_hi:[0,1,1]
	v_pk_fma_f32 v[56:57], v[46:47], v[236:237], v[56:57] op_sel_hi:[0,1,1]
	v_pk_fma_f32 v[60:61], v[46:47], v[128:129], v[60:61] op_sel_hi:[0,1,1]
	v_pk_fma_f32 v[64:65], v[46:47], v[130:131], v[64:65] op_sel_hi:[0,1,1]
	v_pk_fma_f32 v[68:69], v[46:47], v[180:181], v[68:69] op_sel_hi:[0,1,1]
	v_pk_fma_f32 v[72:73], v[46:47], v[182:183], v[72:73] op_sel_hi:[0,1,1]
	ds_read_b32 v173, v253 offset:22356
	ds_read_b64 v[160:161], v253 offset:22360
	ds_read_b128 v[140:143], v253 offset:22368
	ds_read_b128 v[192:195], v253 offset:22384
	ds_read_b64 v[162:163], v253 offset:22440
	ds_read_b128 v[144:147], v253 offset:22448
	ds_read_b128 v[196:199], v253 offset:22464
	s_waitcnt lgkmcnt(7)
	v_fma_f32 v50, v172, v102, v103
	v_pk_fma_f32 v[52:53], v[102:103], v[238:239], v[52:53] op_sel_hi:[0,1,1]
	v_pk_fma_f32 v[56:57], v[102:103], v[240:241], v[56:57] op_sel_hi:[0,1,1]
	v_pk_fma_f32 v[60:61], v[102:103], v[132:133], v[60:61] op_sel_hi:[0,1,1]
	v_pk_fma_f32 v[64:65], v[102:103], v[134:135], v[64:65] op_sel_hi:[0,1,1]
	v_pk_fma_f32 v[68:69], v[102:103], v[184:185], v[68:69] op_sel_hi:[0,1,1]
	v_pk_fma_f32 v[72:73], v[102:103], v[186:187], v[72:73] op_sel_hi:[0,1,1]
	v_pk_fma_f32 v[52:53], v[50:51], v[242:243], v[52:53] op_sel_hi:[0,1,1]
	v_pk_fma_f32 v[56:57], v[50:51], v[244:245], v[56:57] op_sel_hi:[0,1,1]
	v_pk_fma_f32 v[60:61], v[50:51], v[136:137], v[60:61] op_sel_hi:[0,1,1]
	v_pk_fma_f32 v[64:65], v[50:51], v[138:139], v[64:65] op_sel_hi:[0,1,1]
	v_pk_fma_f32 v[68:69], v[50:51], v[188:189], v[68:69] op_sel_hi:[0,1,1]
	v_pk_fma_f32 v[72:73], v[50:51], v[190:191], v[72:73] op_sel_hi:[0,1,1]
	ds_read_b32 v174, v253 offset:22524
	ds_read_b128 v[148:151], v253 offset:22528
	ds_read_b128 v[200:203], v253 offset:22544
	ds_read_b128 v[152:155], v253 offset:22608
	ds_read_b128 v[204:207], v253 offset:22624
	s_waitcnt lgkmcnt(5)
	v_fma_f32 v54, v173, v52, v53
	v_pk_fma_f32 v[56:57], v[52:53], v[160:161], v[56:57] op_sel_hi:[0,1,1]
	v_pk_fma_f32 v[60:61], v[52:53], v[140:141], v[60:61] op_sel_hi:[0,1,1]
	v_pk_fma_f32 v[64:65], v[52:53], v[142:143], v[64:65] op_sel_hi:[0,1,1]
	v_pk_fma_f32 v[68:69], v[52:53], v[192:193], v[68:69] op_sel_hi:[0,1,1]
	v_pk_fma_f32 v[72:73], v[52:53], v[194:195], v[72:73] op_sel_hi:[0,1,1]
	v_pk_fma_f32 v[56:57], v[54:55], v[162:163], v[56:57] op_sel_hi:[0,1,1]
	v_pk_fma_f32 v[60:61], v[54:55], v[144:145], v[60:61] op_sel_hi:[0,1,1]
	v_pk_fma_f32 v[64:65], v[54:55], v[146:147], v[64:65] op_sel_hi:[0,1,1]
	v_pk_fma_f32 v[68:69], v[54:55], v[196:197], v[68:69] op_sel_hi:[0,1,1]
	v_pk_fma_f32 v[72:73], v[54:55], v[198:199], v[72:73] op_sel_hi:[0,1,1]
	ds_read_b32 v248, v253 offset:22692
	ds_read_b64 v[164:165], v253 offset:22696
	ds_read_b128 v[208:211], v253 offset:22704
	ds_read_b64 v[166:167], v253 offset:22776
	ds_read_b128 v[218:221], v253 offset:22784
	s_waitcnt lgkmcnt(5)
	v_fma_f32 v58, v174, v56, v57
	v_pk_fma_f32 v[60:61], v[56:57], v[148:149], v[60:61] op_sel_hi:[0,1,1]
	v_pk_fma_f32 v[64:65], v[56:57], v[150:151], v[64:65] op_sel_hi:[0,1,1]
	v_pk_fma_f32 v[68:69], v[56:57], v[200:201], v[68:69] op_sel_hi:[0,1,1]
	v_pk_fma_f32 v[72:73], v[56:57], v[202:203], v[72:73] op_sel_hi:[0,1,1]
	v_pk_fma_f32 v[60:61], v[58:59], v[152:153], v[60:61] op_sel_hi:[0,1,1]
	v_pk_fma_f32 v[64:65], v[58:59], v[154:155], v[64:65] op_sel_hi:[0,1,1]
	v_pk_fma_f32 v[68:69], v[58:59], v[204:205], v[68:69] op_sel_hi:[0,1,1]
	v_pk_fma_f32 v[72:73], v[58:59], v[206:207], v[72:73] op_sel_hi:[0,1,1]
	ds_read_b32 v249, v253 offset:22860
	ds_read_b128 v[222:225], v253 offset:22864
	ds_read_b128 v[226:229], v253 offset:22944
	s_waitcnt lgkmcnt(3)
	v_fma_f32 v62, v248, v60, v61
	v_pk_fma_f32 v[64:65], v[60:61], v[164:165], v[64:65] op_sel_hi:[0,1,1]
	v_pk_fma_f32 v[68:69], v[60:61], v[208:209], v[68:69] op_sel_hi:[0,1,1]
	v_pk_fma_f32 v[72:73], v[60:61], v[210:211], v[72:73] op_sel_hi:[0,1,1]
	v_pk_fma_f32 v[64:65], v[62:63], v[166:167], v[64:65] op_sel_hi:[0,1,1]
	v_pk_fma_f32 v[68:69], v[62:63], v[218:219], v[68:69] op_sel_hi:[0,1,1]
	v_pk_fma_f32 v[72:73], v[62:63], v[220:221], v[72:73] op_sel_hi:[0,1,1]
	ds_read_b32 v250, v253 offset:23028
	ds_read_b64 v[168:169], v253 offset:23032
	ds_read_b64 v[246:247], v253 offset:23112
	s_waitcnt lgkmcnt(3)
	v_fma_f32 v66, v249, v64, v65
	v_pk_fma_f32 v[68:69], v[64:65], v[222:223], v[68:69] op_sel_hi:[0,1,1]
	v_pk_fma_f32 v[72:73], v[64:65], v[224:225], v[72:73] op_sel_hi:[0,1,1]
	v_pk_fma_f32 v[68:69], v[66:67], v[226:227], v[68:69] op_sel_hi:[0,1,1]
	v_pk_fma_f32 v[72:73], v[66:67], v[228:229], v[72:73] op_sel_hi:[0,1,1]
	ds_read_b32 v251, v253 offset:23196
	s_waitcnt lgkmcnt(1)
	v_fma_f32 v120, v250, v68, v69
	v_pk_fma_f32 v[72:73], v[68:69], v[168:169], v[72:73] op_sel_hi:[0,1,1]
	v_pk_fma_f32 v[72:73], v[120:121], v[246:247], v[72:73] op_sel_hi:[0,1,1]
	s_waitcnt lgkmcnt(0)
	v_fma_f32 v122, v251, v72, v73
	v_add_u32_e32 v252, s88, v80
	v_cvt_pk_bf16_f32 v44, v100, v46
	v_cvt_pk_bf16_f32 v45, v102, v50
	v_cvt_pk_bf16_f32 v46, v52, v54
	v_cvt_pk_bf16_f32 v47, v56, v58
	ds_write_b128 v252, v[44:47] offset:14336
	v_cvt_pk_bf16_f32 v44, v60, v62
	v_cvt_pk_bf16_f32 v45, v64, v66
	v_cvt_pk_bf16_f32 v46, v68, v120
	v_cvt_pk_bf16_f32 v47, v72, v122
	ds_write_b128 v252, v[44:47] offset:14352
	s_setprio 0
